# layer phase 1: half of the workgroups run the short conv before the attention (same work, different order) so bandwidth-bound and issue-bound work overlap across workgroups
# speedup vs baseline: 1.0044x; 1.0044x over previous
; #define LAS __attribute__((address_space(3)))
; __device__ __forceinline__ void run_phase(const Params& p, int ph, LAS unsigned char* lds) {
;     unsigned char* ws = p.ws;
;     if (ph == 0) { phase_convert(p, lds); return; }
;     const int l = (ph - 1) / PH_PER_LAYER, k = (ph - 1) % PH_PER_LAYER;
;     bf16_t* PROJ = (bf16_t*)(ws + WS_PROJ); bf16_t* YCAT = (bf16_t*)(ws + WS_YCAT);
; __global__ void __launch_bounds__(NTHREADS, 2) mega(Params p) {
;     extern __shared__ __attribute__((aligned(16))) unsigned char lds_raw[];
;     LAS unsigned char* lds = (LAS unsigned char*)lds_raw;
;     cg::grid_group grid = cg::this_grid();
;     for (int ph = p.ph_lo; ph < p.ph_hi; ++ph) {
;         if (ph > p.ph_lo) { if (p.ph_hi > 4096) grid.sync();   else grid_barrier((unsigned*)p.ws, (unsigned)(ph - p.ph_lo)); }
.LBB0_1:
	s_mov_b32 s58, s2
	s_add_u32 s2, s0, 0xb0
	s_addc_u32 s3, s1, 0
	s_cmpk_lt_i32 s57, 0x1001
	v_writelane_b32 v252, s2, 0
	s_load_dword s59, s[0:1], 0xb0
	s_load_dwordx2 s[86:87], s[0:1], 0xa0
	v_writelane_b32 v252, s3, 1
	s_cselect_b64 s[2:3], -1, 0
	v_writelane_b32 v252, s2, 2
	s_mov_b32 s91, 0
	s_load_dwordx8 s[76:83], s[0:1], 0x80
	v_writelane_b32 v252, s3, 3
	s_and_b32 s2, s58, 7
	s_xor_b32 s3, s2, 7
	s_waitcnt lgkmcnt(0)
	s_add_i32 s3, s59, s3
	s_lshr_b32 s61, s3, 3
	s_min_u32 s3, s59, 8
	s_lshl_b32 s2, s2, 7
	s_add_u32 s72, s86, s2
	s_addc_u32 s73, s87, 0
	s_add_u32 s94, s86, 0x20601000
	s_addc_u32 s95, s87, 0
	s_add_u32 s24, s86, 0x2e601000
	s_addc_u32 s25, s87, 0
	s_add_u32 s2, s86, 0x28601000
	v_writelane_b32 v252, s3, 4
	s_addc_u32 s3, s87, 0
	s_add_u32 s66, s86, 0x1a601000
	s_addc_u32 s67, s87, 0
	v_writelane_b32 v252, s2, 5
	s_add_u32 s28, s86, 0x33741000
	s_addc_u32 s29, s87, 0
	v_writelane_b32 v252, s3, 6
	s_lshl_b32 s30, s59, 3
	s_lshl_b32 s2, s58, 3
	s_add_u32 s64, s86, 0x12601000
	s_addc_u32 s33, s87, 0
	s_add_u32 s8, s86, 0x33721000
	s_addc_u32 s9, s87, 0
	s_cmpk_lt_i32 s58, 0x200
	v_writelane_b32 v252, s2, 7
	s_cselect_b64 s[2:3], -1, 0
	v_writelane_b32 v252, s2, 8
	s_ashr_i32 s68, s58, 31
	s_ashr_i32 s62, s59, 31
	v_writelane_b32 v252, s3, 9
	s_lshr_b32 s2, s68, 29
	s_add_i32 s2, s58, s2
	s_ashr_i32 s4, s2, 3
	s_and_b32 s2, s2, -8
	s_sub_i32 s5, s58, s2
	s_lshl_b32 s6, s5, 6
	s_add_u32 s10, s86, 0x33701000
	s_addc_u32 s11, s87, 0
	s_add_u32 s69, s86, 0x2601000
	s_addc_u32 s84, s87, 0
	s_cmpk_lt_i32 s58, 0x800
	s_cselect_b64 s[2:3], -1, 0
	v_writelane_b32 v252, s2, 10
	s_lshl_b32 s7, s5, 8
	s_mov_b32 s90, s59
	v_writelane_b32 v252, s3, 11
	s_add_u32 s2, s86, 0x1a601080
	s_addc_u32 s3, s87, 0
	v_writelane_b32 v252, s2, 12
	v_cvt_f32_u32_e32 v1, s59
	v_and_b32_e32 v213, 0x3ff, v0
	v_writelane_b32 v252, s3, 13
	s_add_u32 s2, s86, 0x1a601780
	s_addc_u32 s3, s87, 0
	v_writelane_b32 v252, s2, 14
	s_cmp_lt_u32 s58, 16
	v_rcp_iflag_f32_e32 v1, v1
	v_writelane_b32 v252, s3, 15
	s_cselect_b64 s[2:3], -1, 0
	v_writelane_b32 v252, s2, 16
	v_mul_f32_e32 v1, 0x4f7ffffe, v1
	v_cvt_u32_f32_e32 v1, v1
	v_writelane_b32 v252, s3, 17
	s_lshl_b32 s2, s58, 16
	s_add_u32 s2, s86, s2
	s_addc_u32 s3, s87, 0
	s_add_u32 s2, s2, 0x33601000
	s_addc_u32 s3, s3, 0
	v_writelane_b32 v252, s2, 18
	v_and_b32_e32 v0, 0x3fffffff, v0
	v_mov_b32_e32 v189, 0
	v_writelane_b32 v252, s3, 19
	s_lshl_b32 s2, s58, 11
	s_mov_b32 s12, s2
	s_mov_b32 s3, s91
	v_writelane_b32 v252, s12, 20
	s_lshl_b64 s[2:3], s[2:3], 2
	v_mov_b32_e32 v215, 1
	v_writelane_b32 v252, s13, 21
	s_add_u32 s12, s8, s2
	v_writelane_b32 v252, s8, 22
	s_addc_u32 s13, s9, s3
	s_add_u32 s2, s10, s2
	v_writelane_b32 v252, s9, 23
	v_writelane_b32 v252, s12, 24
	v_mov_b32_e32 v210, 0x3000
	v_mov_b32_e32 v212, 0x358637bd
	v_writelane_b32 v252, s13, 25
	v_writelane_b32 v252, s10, 26
	s_addc_u32 s3, s11, s3
	s_cmp_gt_u32 s59, 16
	v_writelane_b32 v252, s11, 27
	v_writelane_b32 v252, s2, 28
	s_load_dwordx16 s[8:23], s[0:1], 0x40
	v_mov_b64_e32 v[216:217], 0x800
	v_writelane_b32 v252, s3, 29
	s_cselect_b64 s[2:3], -1, 0
	v_writelane_b32 v252, s2, 30
	v_mov_b64_e32 v[250:251], 0x7ff
	v_mov_b64_e32 v[206:207], 0xff
	v_writelane_b32 v252, s3, 31
	s_add_u32 s2, s76, 0x8000000
	v_writelane_b32 v252, s2, 32
	s_addc_u32 s2, s77, 0
	v_writelane_b32 v252, s2, 33
	s_add_u32 s2, s86, 0x16601000
	v_writelane_b32 v252, s2, 34
	s_addc_u32 s2, s87, 0
	v_writelane_b32 v252, s2, 35
	s_add_i32 s2, s59, -16
	s_cmpk_lt_i32 s58, 0x810
	v_writelane_b32 v252, s2, 36
	s_cselect_b64 s[2:3], -1, 0
	v_writelane_b32 v252, s2, 37
	v_mov_b64_e32 v[208:209], 0x100
	v_mov_b32_e32 v214, 0x41b17218
	v_writelane_b32 v252, s3, 38
	s_add_i32 s2, s58, -16
	v_writelane_b32 v252, s2, 39
	s_waitcnt lgkmcnt(0)
	s_add_u32 s85, s20, 0x8000000
	v_writelane_b32 v252, s8, 40
	s_addc_u32 s2, s21, 0
	v_mov_b32_e32 v218, 0x42800000
	v_writelane_b32 v252, s9, 41
	v_writelane_b32 v252, s10, 42
	v_writelane_b32 v252, s11, 43
	v_writelane_b32 v252, s12, 44
	v_writelane_b32 v252, s13, 45
	v_writelane_b32 v252, s14, 46
	v_writelane_b32 v252, s15, 47
	v_writelane_b32 v252, s16, 48
	v_writelane_b32 v252, s17, 49
	v_writelane_b32 v252, s18, 50
	v_writelane_b32 v252, s19, 51
	v_writelane_b32 v252, s20, 52
	v_writelane_b32 v252, s21, 53
	v_writelane_b32 v252, s22, 54
	v_writelane_b32 v252, s23, 55
	v_writelane_b32 v252, s2, 56
	s_add_u32 s2, s86, 0x6601000
	v_writelane_b32 v252, s2, 57
	s_addc_u32 s2, s87, 0
	v_writelane_b32 v252, s2, 58
	s_add_u32 s2, s86, 0x1c601000
	s_addc_u32 s3, s87, 0
	s_add_u32 s12, s86, 0x31601000
	s_addc_u32 s13, s87, 0
	s_add_u32 s34, s86, 0x2201000
	s_addc_u32 s35, s87, 0
	v_writelane_b32 v252, s2, 59
	s_cmpk_lt_i32 s58, 0x100
	v_not_b32_e32 v219, 63
	v_writelane_b32 v252, s3, 60
	s_cselect_b64 s[2:3], -1, 0
	v_writelane_b32 v252, s2, 61
	v_mov_b32_e32 v220, 0xf149f2ca
	v_mov_b32_e32 v221, 0xffffe4e0
	v_writelane_b32 v252, s3, 62
	s_lshl_b32 s2, s5, 5
	s_add_u32 s36, s86, 0x1c01000
	s_addc_u32 s37, s87, 0
	s_add_u32 s8, s86, 0x39861000
	s_addc_u32 s9, s87, 0
	v_writelane_b32 v252, s8, 63
	s_movk_i32 s92, 0x2000
	s_movk_i32 s93, 0x400
	v_writelane_b32 v253, s9, 0
	s_add_u32 s8, s86, 0x34841000
	s_addc_u32 s9, s87, 0
	v_writelane_b32 v253, s8, 1
	s_add_u32 s3, s86, 0x35861000
	s_mov_b32 s60, 0xbfb8aa3b
	v_writelane_b32 v253, s9, 2
	v_writelane_b32 v253, s3, 3
	s_addc_u32 s3, s87, 0
	v_writelane_b32 v253, s3, 4
	s_add_u32 s3, s86, 0x37861000
	v_writelane_b32 v253, s3, 5
	s_addc_u32 s3, s87, 0
	s_add_u32 s8, s86, 0x33841000
	v_writelane_b32 v253, s3, 6
	s_addc_u32 s9, s87, 0
	v_writelane_b32 v253, s8, 7
	s_add_u32 s96, s86, 0x35841000
;     __device__ __forceinline__ bool next(int i0, Unit& u) const {
;         const int i = i0 / nbr; u.br = i0 - i * nbr;
;         const long L = (long)i * G + c; if (L >= nwg) return false;
;         int wgid = (int)L; { const int q = nwg / NXCD, r = nwg % NXCD, xcd = wgid % NXCD, off = wgid / NXCD; wgid = (xcd < r ? xcd * (q + 1) : r * (q + 1) + (xcd - r) * q) + off; }
;         const int nig = WGM * nN, gid = wgid / nig, fm = gid * WGM, gsz = (nM - fm) < WGM ? (nM - fm) : WGM;
;         u.pm = fm + ((wgid % nig) % gsz); u.pn = (wgid % nig) / gsz; return true;
	s_addc_u32 s97, s87, 0
	v_writelane_b32 v253, s9, 8
	s_lshl_b32 s3, s58, 9
	v_writelane_b32 v253, s3, 9
	s_lshl_b32 s3, s59, 9
	s_add_u32 s8, s86, 0x2f601000
	v_writelane_b32 v253, s3, 10
	s_addc_u32 s9, s87, 0
	v_writelane_b32 v253, s8, 11
	s_add_u32 s3, s86, 0x1000
	s_movk_i32 s63, 0x3800
	v_writelane_b32 v253, s9, 12
	v_writelane_b32 v253, s3, 13
	s_addc_u32 s3, s87, 0
	s_cmpk_lt_i32 s58, 0x700
	v_writelane_b32 v253, s3, 14
	s_cselect_b64 s[8:9], -1, 0
	v_writelane_b32 v253, s8, 15
	s_cmp_lt_i32 s5, 0
	s_mul_i32 s3, s5, 0x41
	v_writelane_b32 v253, s9, 16
	s_cselect_b32 s8, s3, s6
	s_mul_i32 s3, s5, 0x101
	s_cselect_b32 s10, s3, s7
	s_movk_i32 s3, 0xe1
	s_cselect_b32 s3, s3, 0xe0
	s_mul_i32 s3, s3, s5
	s_mul_i32 s5, s5, 33
	s_cselect_b32 s11, s5, s2
	s_add_i32 s3, s3, s4
	s_mul_hi_i32 s2, s3, 0x92492493
	s_add_i32 s2, s2, s3
	s_lshr_b32 s5, s2, 31
	s_ashr_i32 s2, s2, 7
	s_add_i32 s2, s2, s5
	s_mul_i32 s5, s2, 0xe0
	s_sub_i32 s3, s3, s5
	s_bfe_u32 s5, s3, 0x3001c
	s_add_i32 s5, s3, s5
	s_and_b32 s6, s5, 0xfff8
	s_sub_i32 s3, s3, s6
	s_lshl_b32 s2, s2, 3
	s_sext_i32_i16 s5, s5
	s_sext_i32_i16 s3, s3
	s_add_i32 s14, s2, s3
	s_ashr_i32 s2, s5, 3
	v_writelane_b32 v253, s2, 17
	s_mov_b32 s6, s14
	s_ashr_i32 s15, s14, 31
	v_writelane_b32 v253, s6, 18
	s_lshr_b32 s2, s5, 3
	s_mov_b32 s70, 0x7f800000
	v_writelane_b32 v253, s7, 19
	s_lshl_b64 s[6:7], s[14:15], 19
	s_add_u32 s6, s66, s6
	s_addc_u32 s7, s67, s7
	s_bfe_i64 s[2:3], s[2:3], 0x100000
	s_lshl_b64 s[2:3], s[2:3], 19
	v_writelane_b32 v253, s2, 20
	s_mov_b32 s74, 0x3f317217
	s_mov_b32 s75, 0x3d800000
	v_writelane_b32 v253, s3, 21
	s_add_u32 s2, s6, 0x40000
	v_writelane_b32 v253, s6, 22
	s_addc_u32 s3, s7, 0
	s_lshl_b32 s14, s58, 2
	v_writelane_b32 v253, s7, 23
	v_writelane_b32 v253, s2, 24
	s_cmpk_lt_i32 s58, 0x368
	s_mov_b32 s71, 0x43000000
	v_writelane_b32 v253, s3, 25
	s_cselect_b64 s[2:3], -1, 0
	v_writelane_b32 v253, s2, 26
	s_add_i32 s5, s59, s58
	s_mov_b32 s65, 0xc2fc0000
	v_writelane_b32 v253, s3, 27
	s_add_u32 s2, s86, 0x1d01000
	v_writelane_b32 v253, s2, 28
	s_addc_u32 s2, s87, 0
	v_writelane_b32 v253, s2, 29
	s_add_u32 s2, s86, 0x1e01000
	v_writelane_b32 v253, s2, 30
	s_addc_u32 s2, s87, 0
	v_writelane_b32 v253, s2, 31
	s_add_u32 s2, s86, 0xa601000
	v_writelane_b32 v253, s2, 32
	s_addc_u32 s2, s87, 0
	s_cmpk_lt_i32 s58, 0x1000
	v_writelane_b32 v253, s2, 33
	s_cselect_b64 s[2:3], -1, 0
	v_writelane_b32 v253, s2, 34
	s_mov_b64 s[88:89], 0x100
	s_mov_b64 s[38:39], 0x40100
	v_writelane_b32 v253, s3, 35
	s_add_i32 s2, s8, s4
	s_ashr_i32 s3, s2, 31
	s_lshr_b32 s3, s3, 27
	s_add_i32 s6, s2, s3
	s_and_b32 s3, s6, 0xffe0
	s_sub_i32 s2, s2, s3
	s_bfe_i32 s3, s2, 0x80000
	s_bfe_u32 s3, s3, 0x3000c
	s_add_i32 s7, s2, s3
	s_and_b32 s3, s7, 0xf8
	s_sub_i32 s8, s2, s3
	s_ashr_i32 s6, s6, 5
	s_bfe_i32 s7, s7, 0x80000
	s_lshl_b32 s6, s6, 3
	s_sext_i32_i16 s7, s7
	s_sext_i32_i8 s8, s8
	s_add_i32 s16, s6, s8
	s_ashr_i32 s6, s7, 3
	v_writelane_b32 v253, s6, 36
	s_lshl_b64 s[8:9], s[90:91], 9
	s_mov_b32 s2, s58
	s_mov_b32 s3, s91
	v_writelane_b32 v253, s8, 37
	s_ashr_i32 s17, s16, 31
	s_lshr_b32 s6, s7, 3
	v_writelane_b32 v253, s9, 38
	s_lshl_b64 s[8:9], s[2:3], 9
	v_writelane_b32 v253, s8, 39
	s_nop 1
	v_writelane_b32 v253, s9, 40
	s_lshl_b64 s[8:9], s[90:91], 11
	v_writelane_b32 v253, s8, 41
	s_nop 1
	v_writelane_b32 v253, s9, 42
	s_lshl_b64 s[8:9], s[16:17], 20
	s_add_u32 s18, s94, s8
	s_mov_b32 s8, s16
	s_addc_u32 s19, s95, s9
	v_writelane_b32 v253, s8, 43
	s_bfe_i64 s[6:7], s[6:7], 0x100000
	s_lshl_b64 s[6:7], s[6:7], 20
	v_writelane_b32 v253, s9, 44
	s_ashr_i32 s8, s16, 3
	s_ashr_i32 s9, s8, 31
	s_lshl_b64 s[8:9], s[8:9], 22
	v_writelane_b32 v253, s8, 45
	s_nop 1
	v_writelane_b32 v253, s9, 46
	v_writelane_b32 v253, s6, 47
	s_nop 1
	v_writelane_b32 v253, s7, 48
	s_add_u32 s6, s18, 0x80000
	v_writelane_b32 v253, s18, 49
	s_addc_u32 s7, s19, 0
	s_nop 0
	v_writelane_b32 v253, s19, 50
	v_writelane_b32 v253, s6, 51
	s_nop 1
	v_writelane_b32 v253, s7, 52
	s_add_i32 s6, s10, s4
	s_ashr_i32 s7, s6, 31
	s_lshr_b32 s7, s7, 25
	s_add_i32 s7, s6, s7
	s_and_b32 s8, s7, 0xff80
	s_sub_i32 s6, s6, s8
	s_bfe_i32 s8, s6, 0x80000
	s_bfe_u32 s8, s8, 0x3000c
	s_add_i32 s8, s6, s8
	s_and_b32 s9, s8, 0xf8
	s_sub_i32 s6, s6, s9
	s_ashr_i32 s7, s7, 7
	s_lshl_b32 s7, s7, 3
	s_sext_i32_i8 s6, s6
	s_add_i32 s4, s11, s4
	s_add_i32 s15, s7, s6
	s_ashr_i32 s6, s4, 31
	s_lshr_b32 s6, s6, 27
	s_add_i32 s9, s4, s6
	s_and_b32 s6, s9, 0xffe0
	s_sub_i32 s4, s4, s6
	s_bfe_i32 s6, s4, 0x80000
	s_bfe_u32 s6, s6, 0x3000c
	s_add_i32 s10, s4, s6
	s_and_b32 s6, s10, 0xf8
	s_sub_i32 s11, s4, s6
	s_ashr_i32 s6, s15, 3
	s_ashr_i32 s7, s6, 31
	s_bfe_i32 s4, s8, 0x80000
	s_lshl_b64 s[6:7], s[6:7], 22
	s_sext_i32_i16 s4, s4
	v_writelane_b32 v253, s6, 53
	s_nop 1
	v_writelane_b32 v253, s7, 54
	s_ashr_i32 s6, s4, 3
	s_lshr_b32 s4, s4, 3
	v_writelane_b32 v253, s6, 55
	s_bfe_i64 s[6:7], s[4:5], 0x100000
	s_lshl_b64 s[6:7], s[6:7], 18
	v_writelane_b32 v253, s6, 56
	s_ashr_i32 s4, s9, 5
	s_lshl_b32 s4, s4, 3
	v_writelane_b32 v253, s7, 57
	s_bfe_i32 s6, s10, 0x80000
	s_sext_i32_i8 s7, s11
	s_sext_i32_i16 s6, s6
	s_add_i32 s8, s4, s7
	v_writelane_b32 v253, s15, 58
	s_lshl_b32 s4, s15, 8
	s_ashr_i32 s9, s8, 31
	v_writelane_b32 v253, s4, 59
	s_ashr_i32 s4, s6, 3
	v_writelane_b32 v253, s4, 60
	s_lshr_b32 s4, s6, 3
	s_lshl_b64 s[6:7], s[8:9], 19
	s_add_u32 s10, s12, s6
	v_writelane_b32 v253, s12, 61
	s_addc_u32 s11, s13, s7
	s_bfe_i64 s[6:7], s[4:5], 0x100000
	v_writelane_b32 v253, s13, 62
	s_lshl_b64 s[12:13], s[6:7], 19
	v_writelane_b32 v253, s12, 63
	s_mov_b32 s4, s8
	s_nop 0
	v_writelane_b32 v254, s13, 0
	s_add_u32 s12, s10, 0x40000
; __device__ void phase_convert(const Params& p, LAS unsigned char* lds) {
;     ...
;     cvt_job(tile, p.w_in, (bf16_t*)(ws + WS_WIN), NL, 1024, NIN, 1024, 0, (size_t)1024 * NIN, (size_t)NP * 1024, (int)blockIdx.x, (int)gridDim.x, 3072);
;     cvt_job(tile, p.wba, (bf16_t*)(ws + WS_WMRG), NL, 512, 1024, 512, 0, (size_t)512 * 1024, (size_t)3 * 1024 * 512, (int)((blockIdx.x + gridDim.x - 104 % gridDim.x) % gridDim.x), (int)gridDim.x);
;     cvt_job(tile, p.wbc, (bf16_t*)(ws + WS_WMRG) + (size_t)1024 * 512, NL, 512, 1024, 512, 0, (size_t)512 * 1024, (size_t)3 * 1024 * 512, (int)((blockIdx.x + gridDim.x - 168 % gridDim.x) % gridDim.x), (int)gridDim.x);
;     cvt_job(tile, p.wbg, (bf16_t*)(ws + WS_WMRG) + (size_t)2 * 1024 * 512, NL, 512, 1024, 512, 0, (size_t)512 * 1024, (size_t)3 * 1024 * 512, (int)((blockIdx.x + gridDim.x - 232 % gridDim.x) % gridDim.x), (int)gridDim.x);
;     cvt_job(tile, p.w_out, (bf16_t*)(ws + WS_WOUT), NL, 1024, 1024, 1024, 0, (size_t)1024 * 1024, (size_t)1024 * 1024, (int)((blockIdx.x + gridDim.x - 40 % gridDim.x) % gridDim.x), (int)gridDim.x);
	v_writelane_b32 v254, s10, 1
	s_addc_u32 s13, s11, 0
	s_lshl_b64 s[8:9], s[8:9], 18
	v_writelane_b32 v254, s11, 2
	v_writelane_b32 v254, s12, 3
	s_add_u32 s8, s24, s8
	s_nop 0
	v_writelane_b32 v254, s13, 4
	v_writelane_b32 v254, s4, 5
	s_nop 1
	v_writelane_b32 v254, s5, 6
	v_writelane_b32 v254, s24, 7
	s_addc_u32 s9, s25, s9
	s_lshl_b64 s[6:7], s[6:7], 18
	v_writelane_b32 v254, s25, 8
	v_writelane_b32 v254, s6, 9
	s_nop 1
	v_writelane_b32 v254, s7, 10
	s_add_u32 s6, s8, 0x20000
	v_writelane_b32 v254, s8, 11
	s_addc_u32 s7, s9, 0
	s_nop 0
	v_writelane_b32 v254, s9, 12
	v_writelane_b32 v254, s6, 13
	s_nop 1
	v_writelane_b32 v254, s7, 14
	v_sub_co_u32_e64 v2, s[6:7], 0, s59
	s_nop 0
	v_readfirstlane_b32 s4, v2
	v_writelane_b32 v254, s6, 15
	s_nop 1
	v_writelane_b32 v254, s7, 16
	v_readfirstlane_b32 s6, v1
	s_mul_i32 s4, s4, s6
	s_mul_hi_u32 s4, s6, s4
	s_add_i32 s6, s6, s4
	s_mul_hi_u32 s4, s6, 0x68
	s_mul_i32 s4, s4, s59
	s_sub_i32 s4, 0x68, s4
	s_sub_i32 s7, s4, s59
	s_cmp_ge_u32 s4, s59
	s_cselect_b32 s4, s7, s4
	s_sub_i32 s7, s4, s59
	s_cmp_ge_u32 s4, s59
	s_cselect_b32 s4, s7, s4
	s_sub_i32 s4, s5, s4
	s_mul_hi_u32 s7, s4, s6
	s_mul_i32 s7, s7, s59
	s_sub_i32 s4, s4, s7
	s_sub_i32 s7, s4, s59
	s_cmp_ge_u32 s4, s59
	s_cselect_b32 s4, s7, s4
	s_sub_i32 s7, s4, s59
	s_cmp_ge_u32 s4, s59
	s_cselect_b32 s8, s7, s4
	s_mul_hi_u32 s4, s6, 0xa8
	s_cmp_lt_i32 s8, 64
	s_mul_i32 s4, s4, s59
	s_cselect_b64 s[10:11], -1, 0
	s_sub_i32 s4, 0xa8, s4
	s_sub_i32 s7, s4, s59
	s_cmp_ge_u32 s4, s59
	s_cselect_b32 s4, s7, s4
	s_sub_i32 s7, s4, s59
	s_cmp_ge_u32 s4, s59
	s_cselect_b32 s4, s7, s4
	s_sub_i32 s4, s5, s4
	s_mul_hi_u32 s7, s4, s6
	s_mul_i32 s7, s7, s59
	s_sub_i32 s4, s4, s7
	s_sub_i32 s7, s4, s59
	s_cmp_ge_u32 s4, s59
	s_cselect_b32 s4, s7, s4
	s_sub_i32 s7, s4, s59
	s_cmp_ge_u32 s4, s59
	s_cselect_b32 s9, s7, s4
	s_mul_hi_u32 s4, s6, 0xe8
	v_writelane_b32 v254, s10, 17
	s_cmp_lt_i32 s9, 64
	s_mul_i32 s4, s4, s59
	v_writelane_b32 v254, s11, 18
	s_cselect_b64 s[10:11], -1, 0
	s_sub_i32 s4, 0xe8, s4
	s_sub_i32 s7, s4, s59
	s_cmp_ge_u32 s4, s59
	s_cselect_b32 s4, s7, s4
	s_sub_i32 s7, s4, s59
	s_cmp_ge_u32 s4, s59
	s_cselect_b32 s4, s7, s4
	s_sub_i32 s4, s5, s4
	s_mul_hi_u32 s7, s4, s6
	s_mul_i32 s7, s7, s59
	s_sub_i32 s4, s4, s7
	s_sub_i32 s7, s4, s59
	s_cmp_ge_u32 s4, s59
	s_cselect_b32 s4, s7, s4
	s_sub_i32 s7, s4, s59
	v_writelane_b32 v254, s10, 19
	s_cmp_ge_u32 s4, s59
	v_mbcnt_lo_u32_b32 v1, -1, 0
	v_writelane_b32 v254, s11, 20
	s_cselect_b32 s10, s7, s4
	s_mul_hi_u32 s4, s6, 40
	s_cmp_lt_i32 s10, 64
	s_mul_i32 s4, s4, s59
	s_cselect_b64 s[12:13], -1, 0
	s_sub_i32 s4, 40, s4
	s_sub_i32 s7, s4, s59
	s_cmp_ge_u32 s4, s59
	s_cselect_b32 s4, s7, s4
	s_sub_i32 s7, s4, s59
	s_cmp_ge_u32 s4, s59
	s_cselect_b32 s4, s7, s4
	s_sub_i32 s4, s5, s4
	s_mul_hi_u32 s5, s4, s6
	s_mul_i32 s5, s5, s59
	s_sub_i32 s4, s4, s5
	s_sub_i32 s5, s4, s59
	s_cmp_ge_u32 s4, s59
	s_cselect_b32 s4, s5, s4
	s_sub_i32 s5, s4, s59
	s_cmp_ge_u32 s4, s59
	s_cselect_b32 s4, s5, s4
	v_writelane_b32 v254, s12, 21
	s_cmpk_lt_i32 s4, 0x80
	s_cselect_b64 s[6:7], -1, 0
	v_writelane_b32 v254, s13, 22
	v_writelane_b32 v254, s6, 23
	v_mbcnt_hi_u32_b32 v211, -1, v1
	s_nop 0
	v_writelane_b32 v254, s7, 24
	s_lshl_b64 s[6:7], s[90:91], 13
	v_writelane_b32 v254, s6, 25
	s_nop 1
	v_writelane_b32 v254, s7, 26
	s_lshl_b64 s[6:7], s[90:91], 12
	v_writelane_b32 v254, s6, 27
	s_nop 1
	v_writelane_b32 v254, s7, 28
	s_add_u32 s6, s86, 0x800
	s_addc_u32 s7, s87, 0
	v_writelane_b32 v254, s6, 29
	s_sub_i32 s5, s14, 64
	s_ashr_i32 s31, s30, 31
	v_writelane_b32 v254, s7, 30
	v_writelane_b32 v254, s14, 31
	v_writelane_b32 v254, s5, 32
	s_lshl_b32 s5, s59, 2
	v_writelane_b32 v254, s5, 33
	s_sub_i32 s5, s5, 64
	v_writelane_b32 v254, s5, 34
	s_lshl_b32 s5, s59, 11
	v_writelane_b32 v254, s5, 35
	v_writelane_b32 v254, s8, 36
	s_lshl_b32 s5, s8, 2
	v_writelane_b32 v254, s5, 37
	v_writelane_b32 v254, s9, 38
	s_lshl_b32 s5, s9, 2
	v_writelane_b32 v254, s5, 39
	v_writelane_b32 v254, s10, 40
	s_lshl_b32 s5, s10, 2
	v_writelane_b32 v254, s5, 41
	v_writelane_b32 v254, s4, 42
	s_lshl_b32 s4, s4, 2
	v_writelane_b32 v254, s4, 43
	s_lshl_b64 s[4:5], s[30:31], 2
	s_load_dwordx16 s[8:23], s[0:1], 0x0
	v_writelane_b32 v254, s4, 44
	s_nop 1
	v_writelane_b32 v254, s5, 45
	s_lshl_b64 s[4:5], s[30:31], 11
	v_writelane_b32 v254, s4, 46
	s_nop 1
	v_writelane_b32 v254, s5, 47
	s_lshl_b64 s[4:5], s[2:3], 13
	s_waitcnt lgkmcnt(0)
	s_add_u32 s0, s8, s4
	v_writelane_b32 v254, s8, 48
	s_addc_u32 s1, s9, s5
	v_writelane_b32 v255, s0, 0
	v_writelane_b32 v254, s9, 49
	v_writelane_b32 v254, s10, 50
	v_writelane_b32 v255, s1, 1
	s_lshl_b64 s[0:1], s[2:3], 12
	s_lshl_b64 s[2:3], s[90:91], 15
	v_writelane_b32 v255, s2, 2
	v_writelane_b32 v254, s11, 51
	s_mov_b32 s4, s30
	v_writelane_b32 v255, s3, 3
	s_lshl_b64 s[2:3], s[90:91], 14
	s_add_u32 s0, s86, s0
	s_addc_u32 s1, s87, s1
	v_writelane_b32 v255, s2, 4
	s_add_u32 s0, s0, 0x1a601000
	s_addc_u32 s1, s1, 0
	v_writelane_b32 v255, s3, 5
	v_writelane_b32 v255, s0, 6
	s_add_i32 s2, 0, 0x10400
	v_writelane_b32 v254, s12, 52
	v_writelane_b32 v255, s1, 7
	s_mul_hi_u32 s1, s59, 0x600
	s_mul_i32 s0, s59, 0x600
	v_writelane_b32 v255, s0, 8
	v_writelane_b32 v254, s13, 53
	v_writelane_b32 v254, s14, 54
	v_writelane_b32 v255, s1, 9
	s_mul_hi_u32 s1, s59, 0x6000
	s_mul_i32 s0, s59, 0x6000
	v_writelane_b32 v255, s0, 10
	v_writelane_b32 v254, s15, 55
	v_writelane_b32 v254, s16, 56
	v_writelane_b32 v255, s1, 11
	s_mul_hi_u32 s1, s59, 0x3000
	s_mul_i32 s0, s59, 0x3000
	v_writelane_b32 v255, s0, 12
	v_writelane_b32 v254, s17, 57
	v_writelane_b32 v254, s18, 58
	v_writelane_b32 v255, s1, 13
	v_writelane_b32 v255, s2, 14
	s_add_i32 s2, 0, 0x1040c
	v_writelane_b32 v255, s2, 15
	s_add_i32 s2, 0, 0x10408
	v_writelane_b32 v255, s2, 16
	v_cmp_eq_u32_e64 s[2:3], 0, v213
	v_writelane_b32 v254, s19, 59
	v_writelane_b32 v254, s20, 60
	v_writelane_b32 v255, s2, 17
	v_writelane_b32 v254, s21, 61
	v_writelane_b32 v254, s22, 62
	v_writelane_b32 v255, s3, 18
	v_cmp_eq_u32_e64 s[2:3], 0, v0
	v_writelane_b32 v254, s23, 63
	s_mov_b32 s0, 0xffff0000
	v_writelane_b32 v255, s2, 19
	s_mov_b32 s1, 0x800000
	s_mov_b32 s16, s56
	v_writelane_b32 v255, s3, 20
	v_writelane_b32 v255, s66, 21
	s_mov_b64 s[2:3], 0x180
	s_nop 0
	v_writelane_b32 v255, s67, 22
	v_writelane_b32 v255, s28, 23
	s_nop 1
	v_writelane_b32 v255, s29, 24
	v_writelane_b32 v255, s4, 25
	s_nop 1
	v_writelane_b32 v255, s5, 26
	v_writelane_b32 v255, s33, 27
	v_writelane_b32 v255, s68, 28
	v_writelane_b32 v255, s69, 29
	v_writelane_b32 v255, s84, 30
	v_writelane_b32 v255, s34, 31
	v_writelane_b32 v255, s35, 32
	v_writelane_b32 v255, s36, 33
	v_writelane_b32 v255, s37, 34
	v_writelane_b32 v255, s72, 35
	s_nop 1
	v_writelane_b32 v255, s73, 36
	v_writelane_b32 v255, 0, 63
	s_branch .LBB0_4

; #define LAS __attribute__((address_space(3)))
; __device__ __forceinline__ int fresh_tid() { int t = threadIdx.x; asm volatile("" : "+v"(t)); return t; }
; __device__ void attn_mfma(const Params& p, int l, const bf16_t* proj, bf16_t* y0, LAS unsigned char* lds) {
;     constexpr int KP = 72, VP = 392;
;     LAS bf16_t* Ks = (LAS bf16_t*)lds;
;     LAS bf16_t* Vt = (LAS bf16_t*)(lds + 384 * KP * 2);
;     const int tid = fresh_tid(), lane = tid & 63, wv = tid >> 6, fr = lane & 15, g = lane >> 4;
;     for (int it = blockIdx.x; it < 256; it += gridDim.x) {
;         const int n = it >> 1, hk = it & 1, kbase = (n - 1) * 128;
;         __syncthreads();
;         {
;             u32x4 kreg[6], va[3], vb[3];
; #pragma unroll
;             for (int q = 0; q < 6; ++q) { const int c = tid + q * NTHREADS, row = c >> 3, part = c & 7, s = kbase + row;
;                 kreg[q] = (u32x4){0u, 0u, 0u, 0u}; if (s >= 0 && s < SEQ) kreg[q] = *(const u32x4*)(proj + (size_t)s * NP + AK + hk * 64 + part * 8); }
; #pragma unroll
;             for (int q = 0; q < 3; ++q) { const int c = tid + q * NTHREADS, pr = c >> 3, part = c & 7, s = kbase + pr * 2;
;                 va[q] = (u32x4){0u, 0u, 0u, 0u}; vb[q] = (u32x4){0u, 0u, 0u, 0u};
;                 if (s >= 0 && s < SEQ) { va[q] = *(const u32x4*)(proj + (size_t)s * NP + AV + hk * 64 + part * 8); vb[q] = *(const u32x4*)(proj + (size_t)(s + 1) * NP + AV + hk * 64 + part * 8); } }
; #pragma unroll
;             for (int q = 0; q < 6; ++q) { const int c = tid + q * NTHREADS, row = c >> 3, part = c & 7; *(LAS u32x4*)(Ks + row * KP + part * 8) = kreg[q]; }
; #pragma unroll
;             for (int q = 0; q < 3; ++q) { const int c = tid + q * NTHREADS, pr = c >> 3, part = c & 7; const u32x4 a = va[q], b = vb[q];
; #pragma unroll
;                 for (int e = 0; e < 4; ++e) {
;                     *(LAS unsigned*)(Vt + (part * 8 + 2 * e) * VP + pr * 2) = (a[e] & 0xffffu) | (b[e] << 16);
;                     *(LAS unsigned*)(Vt + (part * 8 + 2 * e + 1) * VP + pr * 2) = (a[e] >> 16) | (b[e] & 0xffff0000u); } }
;         }
.Lk1_bb457:
	v_readlane_b32 s4, v252, 61
	v_readlane_b32 s5, v252, 62
	v_readlane_b32 s20, v253, 11
	s_waitcnt vmcnt(0)
	v_mov_b32_e32 v0, v213
	s_andn2_b64 vcc, exec, s[4:5]
	v_readlane_b32 s18, v253, 10
	v_readlane_b32 s21, v253, 12
	v_readlane_b32 s19, v254, 35
	s_movk_i32 s66, 0x1000
	s_movk_i32 s22, 0x4000
	s_movk_i32 s23, 0x1c00
	s_mov_b64 s[24:25], 0x1800
	v_readlane_b32 s8, v255, 63
	s_bitcmp1_b32 s58, 3
	s_cbranch_scc0 .Lk1_noswap
	s_cmp_lg_u32 s8, 0
	s_cbranch_scc1 .Lk1_noswap
	v_writelane_b32 v255, 1, 63
	s_branch .LBB0_480
.Lk1_noswap:
	s_cbranch_vccnz .LBB0_480
	v_and_b32_e32 v6, 64, v211
	v_xor_b32_e32 v5, 16, v211
	v_add_u32_e32 v6, 64, v6
	v_cmp_lt_i32_e32 vcc, v5, v6
	v_bfe_u32 v2, v0, 4, 2
	v_readlane_b32 s4, v254, 7
	v_cndmask_b32_e32 v5, v211, v5, vcc
	v_add_u32_e32 v8, 0x600, v0
	v_lshlrev_b32_e32 v110, 3, v2
	v_mov_b32_e32 v111, v189
	v_lshlrev_b32_e32 v121, 2, v5
	v_xor_b32_e32 v5, 32, v211
	v_readlane_b32 s5, v254, 8
	v_ashrrev_i32_e32 v125, 3, v8
	v_add_u32_e32 v8, 0x800, v0
	v_and_b32_e32 v1, 15, v0
	v_lshlrev_b32_e32 v3, 3, v0
	v_ashrrev_i32_e32 v109, 7, v0
	v_and_b32_e32 v120, 0x4f, v0
	v_cmp_lt_i32_e32 vcc, v5, v6
	v_lshl_add_u64 v[112:113], s[4:5], 0, v[110:111]
	v_ashrrev_i32_e32 v111, 3, v0
	v_add_u32_e32 v6, 0x200, v0
	v_add_u32_e32 v7, 0x400, v0
	v_ashrrev_i32_e32 v126, 3, v8
	v_add_u32_e32 v8, 0xa00, v0
	v_ashrrev_i32_e32 v0, 2, v0
	v_and_b32_e32 v128, -2, v0
	v_ashrrev_i32_e32 v0, 2, v6
	v_and_b32_e32 v108, 56, v3
	v_ashrrev_i32_e32 v123, 3, v6
	v_ashrrev_i32_e32 v124, 3, v7
	v_ashrrev_i32_e32 v127, 3, v8
	v_and_b32_e32 v129, -2, v0
	v_ashrrev_i32_e32 v0, 2, v7
	s_movk_i32 s4, 0x90
	v_lshl_add_u32 v3, v108, 1, 0
	v_and_b32_e32 v130, -2, v0
	v_mul_lo_u32 v0, v111, s4
	v_mul_lo_u32 v6, v123, s4
	v_mul_lo_u32 v7, v124, s4
	v_mul_lo_u32 v8, v125, s4
	v_mul_lo_u32 v9, v126, s4
	v_mul_lo_u32 v10, v127, s4
	s_movk_i32 s4, 0x30e
	v_lshl_add_u32 v4, v2, 4, 0
	v_lshlrev_b32_e32 v2, 2, v2
	v_cndmask_b32_e32 v5, v211, v5, vcc
	v_mad_u32_u24 v11, v108, s4, v3
	s_movk_i32 s4, 0x310
	v_mov_b32_e32 v13, 0x3100
	v_mov_b32_e32 v14, 0x6200
	v_mov_b32_e32 v15, 0x9300
	v_lshlrev_b32_e32 v122, 2, v5
	v_sub_u32_e32 v5, v4, v110
	v_lshl_add_u32 v131, v128, 1, v11
	v_lshl_add_u32 v132, v129, 1, v11
	v_lshl_add_u32 v133, v130, 1, v11
	v_mul_u32_u24_e32 v11, 0x90, v1
	v_mul_u32_u24_e32 v12, 0x310, v1
	v_mad_u32_u24 v13, v1, s4, v13
	v_mad_u32_u24 v14, v1, s4, v14
	v_mad_u32_u24 v1, v1, s4, v15
	v_sub_u32_e32 v2, v120, v2
	s_lshl_b32 s10, s26, 3
	v_add_u32_e32 v134, 0x80, v2
	v_add_u32_e32 v135, v3, v0
	v_add_u32_e32 v136, v3, v6
	v_add_u32_e32 v137, v3, v7
	v_add_u32_e32 v138, v3, v8
	v_add_u32_e32 v139, v3, v9
	v_add_u32_e32 v140, v3, v10
	v_add_u32_e32 v141, v4, v11
	v_add_u32_e32 v142, v5, v12
	v_add_u32_e32 v143, v5, v13
	v_add_u32_e32 v144, v5, v14
	v_add_u32_e32 v145, v5, v1
	v_and_b32_e32 v185, 64, v120
	v_mul_u32_u24_e32 v186, 0x90, v185
	v_add_u32_e32 v174, v141, v186
	v_lshlrev_b32_e32 v186, 1, v185
	v_add_u32_e32 v186, 0xd800, v186
	v_add_u32_e32 v175, v142, v186
	v_add_u32_e32 v176, v143, v186
	v_add_u32_e32 v177, v144, v186
	v_add_u32_e32 v178, v145, v186
	v_sub_u32_e32 v187, v134, v185
	v_cvt_f32_u32_e32 v179, v187
	s_mov_b32 s11, s58

; __device__ __forceinline__ void run_phase(const Params& p, int ph, LAS unsigned char* lds) {
;     ...
;     case 1: { attn_mfma(p, l, PROJ, YCAT, lds); conv_naive(p, l, PROJ, YCAT); __syncthreads(); gla_pass1(p, l, PROJ, lds); } break;
.LBB0_480:
	v_readlane_b32 s8, v255, 63
	s_cmp_eq_u32 s8, 2
	s_cbranch_scc0 .Lk1_doconv
	v_writelane_b32 v255, 0, 63
	s_branch .Lk1_after_conv

; __device__ __forceinline__ int fresh_tid() { int t = threadIdx.x; asm volatile("" : "+v"(t)); return t; }
; __device__ void gla_pass1(const Params& p, int l, const bf16_t* proj, LAS unsigned char* lds) {
;     ...
;     for (int it = blockIdx.x; it < NSEG * 8; it += gridDim.x) {
;         const int seg = it >> 3, h = (it >> 1) & 3, dir = it & 1;
;         const int tid = fresh_tid(), lane = tid & 63, wv = tid >> 6, fr = lane & 15, g = lane >> 4;
; __device__ __forceinline__ void run_phase(const Params& p, int ph, LAS unsigned char* lds) {
;     ...
;     case 1: { attn_mfma(p, l, PROJ, YCAT, lds); conv_naive(p, l, PROJ, YCAT); __syncthreads(); gla_pass1(p, l, PROJ, lds); } break;
.Lk1_after_conv:
	v_readlane_b32 s8, v255, 63
	s_cmp_eq_u32 s8, 1
	s_cbranch_scc0 .Lk1_topass1
	v_writelane_b32 v255, 2, 63
	s_branch .Lk1_bb457
.Lk1_topass1:
	v_readlane_b32 s4, v252, 8
	v_readlane_b32 s5, v252, 9
	s_mov_b32 s72, s26
	s_andn2_b64 vcc, exec, s[4:5]
	s_waitcnt lgkmcnt(0)
	s_barrier
	s_cbranch_vccnz .LBB0_492
	s_lshl_b32 s26, s72, 1
	s_mov_b32 s27, s58
	s_branch .LBB0_486
